# one static s_setprio 1 for waves 4-7 during the attention phase (reset at phase exit), on top of v61
# baseline (speedup 1.0000x reference)
; #define LAS __attribute__((address_space(3)))
; __global__ void __launch_bounds__(512, 2) mega(Params p, int ph_lo, int ph_hi) {
;     ...
;     PHASE_BEGIN
;         LAS unsigned char* KS = lds + wave * (2 * 32 * HP * 2); LAS unsigned char* VS = KS + 32 * HP * 2;
;         for (int it = 0; it * G < 1024; ++it) {
;             const int item = (G == 256) ? ((bid & 7) * 128 + it * 32 + (bid >> 3)) : (bid + it * G);
;             if (item >= 1024) break;
;             const int b = item >> 9, h = (item >> 5) & 15, n = item & 31;
;             const int r0 = wave, r1 = wave + 8;
;             QTile t0, t1;
.LBB0_777:
	s_cmp_lt_u32 s96, 4
	s_cbranch_scc1 .Lat_noprio
	s_setprio 1

; #define LAS __attribute__((address_space(3)))
; __device__ __forceinline__ void lds_wait() { asm volatile("s_waitcnt lgkmcnt(0)" ::: "memory"); }
; __device__ __forceinline__ void transpose_item(const float* W, int K, int N, bf16_t* WT, int gate, const float* kscale, LAS float* scr, int item, int lane) {
;     const int nblk = N / 64, kb = item / nblk, nb = item % nblk, k0 = 64 * kb, n0 = 64 * nb;
;     const int c4 = (lane & 15) * 4, kr = lane >> 4;
;     f32x4 v[16];
; #pragma unroll
;     for (int i = 0; i < 16; ++i) v[i] = __builtin_nontemporal_load((const f32x4*)(W + (size_t)(k0 + 4 * i + kr) * N + n0 + c4));
; #pragma unroll
;     for (int i = 0; i < 16; ++i) { LAS float* d = scr + (4 * i + kr) * 65 + c4; d[0] = v[i][0]; d[1] = v[i][1]; d[2] = v[i][2]; d[3] = v[i][3]; }
;     lds_wait();
;     const int c = lane & 7;
;     f32x4 k0v = {1.f, 1.f, 1.f, 1.f}, k1v = k0v;
;     if (kscale) { k0v = *(const f32x4*)(kscale + k0 + 8 * c); k1v = *(const f32x4*)(kscale + k0 + 8 * c + 4); }
; #pragma unroll
;     for (int j = 0; j < 8; ++j) { const int n = (lane >> 3) + 8 * j; const LAS float* s = scr + (8 * c) * 65 + n;
; __global__ void __launch_bounds__(512, 2) mega(Params p, int ph_lo, int ph_hi) {
;     ...
;         __syncthreads();
;         int lane3; asm volatile("v_mbcnt_lo_u32_b32 %0, -1, 0\n\tv_mbcnt_hi_u32_b32 %0, -1, %0" : "=v"(lane3));
;         transpose_job(p.w_o, DM, DM, WB, -1, nullptr, lds, gw, NGW, wave, lane3);
.LBB0_812:
	s_setprio 0
	s_mul_i32 s0, s96, 0xfffffd00
	s_add_i32 s3, s3, s0
	s_cmpk_gt_i32 s54, 0x3ff
	s_waitcnt vmcnt(0)
	s_barrier
	v_mbcnt_lo_u32_b32 v4, -1, 0
	v_mbcnt_hi_u32_b32 v4, -1, v4
	s_nop 0
	v_ashrrev_i32_e32 v10, 4, v4
	v_and_b32_e32 v8, 7, v4
	v_ashrrev_i32_e32 v11, 3, v4
	s_cbranch_scc1 .LBB0_815
	v_lshlrev_b32_e32 v0, 4, v4
	v_readlane_b32 s4, v253, 0
	v_and_b32_e32 v2, 0xf0, v0
	v_mov_b32_e32 v3, 0
	v_readlane_b32 s6, v253, 2
	v_readlane_b32 s7, v253, 3
	s_movk_i32 s0, 0x104
	v_add_u32_e32 v6, s3, v2
	v_lshl_add_u64 v[0:1], s[6:7], 0, v[2:3]
	v_mul_lo_u32 v7, v10, s0
	v_mul_u32_u24_e32 v2, 0x820, v8
	v_lshlrev_b32_e32 v5, 2, v11
	v_add3_u32 v5, s3, v2, v5
	v_lshlrev_b32_e32 v2, 4, v8
	v_add_u32_e32 v6, v6, v7
	v_lshl_add_u64 v[2:3], s[36:37], 0, v[2:3]
	s_lshl_b32 s0, s54, 6
	v_add_u32_e32 v7, 0x410, v6
	v_add_u32_e32 v9, 0x418, v6
	v_add_u32_e32 v12, 0x820, v6
	v_add_u32_e32 v13, 0x828, v6
	v_add_u32_e32 v14, 0xc30, v6
	v_add_u32_e32 v15, 0xc38, v6
	v_add_u32_e32 v16, 0x1040, v6
	v_add_u32_e32 v17, 0x1048, v6
	v_add_u32_e32 v18, 0x1450, v6
	v_add_u32_e32 v19, 0x1458, v6
	v_add_u32_e32 v20, 0x1860, v6
	v_add_u32_e32 v21, 0x1868, v6
	v_add_u32_e32 v22, 0x1c70, v6
	v_add_u32_e32 v23, 0x1c78, v6
	v_add_u32_e32 v24, 0x2080, v6
	v_add_u32_e32 v25, 0x2088, v6
	v_add_u32_e32 v26, 0x2490, v6
	v_add_u32_e32 v27, 0x2498, v6
	v_add_u32_e32 v28, 0x28a0, v6
	v_add_u32_e32 v29, 0x28a8, v6
	v_add_u32_e32 v30, 0x2cb0, v6
	v_add_u32_e32 v31, 0x2cb8, v6
	v_add_u32_e32 v32, 0x30c0, v6
	v_add_u32_e32 v33, 0x30c8, v6
	v_add_u32_e32 v34, 0x34d0, v6
	v_add_u32_e32 v35, 0x34d8, v6
	v_add_u32_e32 v36, 0x38e0, v6
	v_add_u32_e32 v37, 0x38e8, v6
	v_add_u32_e32 v38, 0x3cf0, v6
	v_add_u32_e32 v39, 0x3cf8, v6
	v_add_u32_e32 v40, 0x400, v5
	s_mov_b32 s1, s54
	v_readlane_b32 s5, v253, 1
	v_readlane_b32 s8, v253, 4
	v_readlane_b32 s9, v253, 5
	v_readlane_b32 s10, v253, 6
	v_readlane_b32 s11, v253, 7
